# layer-0 in-projection phase: workgroups 0..31 keep only their memory tile; their second tiles go to workgroups 480..511 and their third tiles to 448..479
# baseline (speedup 1.0000x reference)
; __global__ void __launch_bounds__(256, 2) fwd_megakernel(Params p) {
;     ...
;     const int n_mem = 2 * 2 * 8, n_proj = (NT / 128) * 10;
;     for (int t = blockIdx.x; t < n_mem + n_proj; t += gridDim.x) {
;       f32x16 acc[2][2];
;       if (t < n_mem) {
;         const int l = t >> 4, tm = (t >> 3) & 1, tn = t & 7;
.LBB0_164:
	s_add_i32 s53, s53, s50
	s_add_i32 s39, s39, s40
	s_add_i32 s41, s41, s42
	s_cmpk_lg_u32 s50, 0x200
	s_cbranch_scc1 .Lp1_keep
	s_cmpk_lt_i32 s53, 0x200
	s_cbranch_scc1 .Lp1_keep
	s_cmpk_ge_i32 s53, 0x600
	s_cbranch_scc1 .Lp1_keep
	s_cmpk_lt_u32 s78, 32
	s_cbranch_scc0 .Lp1_a
	s_movk_i32 s53, 0x5c0
	s_branch .Lp1_keep
.Lp1_a:
	s_cmpk_lt_i32 s53, 0x400
	s_cbranch_scc1 .Lp1_keep
	s_sub_u32 s98, s78, 0x1c0
	s_cmpk_lt_u32 s98, 64
	s_cbranch_scc0 .Lp1_keep
	s_sub_u32 s99, s53, s78
	s_cmpk_eq_u32 s99, 0x400
	s_cbranch_scc1 .Lp1_remap
	s_movk_i32 s53, 0x5c0
	s_branch .Lp1_keep
.Lp1_remap:
	s_add_u32 s53, s98, 0x1e0
	s_cmpk_lt_u32 s98, 32
	s_cselect_b32 s99, 0x220, 0
	s_add_u32 s53, s53, s99
	s_lshl_b32 s39, s53, 4
	s_lshl_b32 s41, s53, 7
